# stack: attn_sample LDS read batching with 4 split f32 accumulators per dot product, plus attention p_k p_v tail unrolled
# baseline (speedup 1.0000x reference)
.LBB0_529:
	s_mov_b32 s8, 0x3e0f83e1
	v_mul_hi_i32 v5, v6, s8
	v_lshrrev_b32_e32 v7, 31, v5
	v_ashrrev_i32_e32 v5, 5, v5
	v_add_u32_e32 v5, v5, v7
	s_movk_i32 s8, 0xff7c
	v_mad_u64_u32 v[8:9], s[8:9], v5, s8, v[6:7]
	v_ashrrev_i32_e32 v7, 2, v5
	v_sub_u32_e32 v7, v7, v8
	v_add_u32_e32 v7, 0x80, v7
	v_cmp_gt_u32_e32 vcc, s35, v7
	v_mov_b32_e32 v9, 0xff800000
	s_and_saveexec_b64 s[8:9], vcc
	s_cbranch_execz .LBB0_528
	s_mov_b32 s14, 0xffff79f0
	v_mad_u64_u32 v[12:13], s[14:15], v5, s14, v[0:1]
	v_lshl_add_u32 v9, v5, 8, 0
	v_mov_b32_e32 v10, 0
	v_mov_b32_e32 v198, 0
	v_mov_b32_e32 v199, 0
	v_mov_b32_e32 v200, 0
	s_mov_b32 s14, 0
.LBB0_531:
	v_add_u32_e32 v11, s14, v9
	v_add_u32_e32 v11, 0x10c20, v11
	v_add_u32_e32 v13, s14, v12
	ds_read_b128 v[146:149], v11
	ds_read_b128 v[150:153], v11 offset:16
	ds_read2_b32 v[154:155], v13 offset1:1
	ds_read2_b32 v[156:157], v13 offset0:2 offset1:3
	ds_read2_b32 v[158:159], v13 offset0:4 offset1:5
	ds_read2_b32 v[160:161], v13 offset0:6 offset1:7
	ds_read_b128 v[182:185], v11 offset:32
	ds_read_b128 v[186:189], v11 offset:48
	ds_read2_b32 v[190:191], v13 offset0:8 offset1:9
	ds_read2_b32 v[192:193], v13 offset0:10 offset1:11
	ds_read2_b32 v[194:195], v13 offset0:12 offset1:13
	ds_read2_b32 v[196:197], v13 offset0:14 offset1:15
	s_add_i32 s14, s14, 64
	s_cmpk_eq_i32 s14, 0x100
	s_waitcnt lgkmcnt(6)
	v_fmac_f32_e32 v10, v146, v154
	v_fmac_f32_e32 v198, v147, v155
	v_fmac_f32_e32 v199, v148, v156
	v_fmac_f32_e32 v200, v149, v157
	v_fmac_f32_e32 v10, v150, v158
	v_fmac_f32_e32 v198, v151, v159
	v_fmac_f32_e32 v199, v152, v160
	v_fmac_f32_e32 v200, v153, v161
	s_waitcnt lgkmcnt(0)
	v_fmac_f32_e32 v10, v182, v190
	v_fmac_f32_e32 v198, v183, v191
	v_fmac_f32_e32 v199, v184, v192
	v_fmac_f32_e32 v200, v185, v193
	v_fmac_f32_e32 v10, v186, v194
	v_fmac_f32_e32 v198, v187, v195
	v_fmac_f32_e32 v199, v188, v196
	v_fmac_f32_e32 v200, v189, v197
	s_cbranch_scc0 .LBB0_531
	v_add_f32_e32 v10, v10, v198
	v_add_f32_e32 v199, v199, v200
	s_nop 0
	v_add_f32_e32 v10, v10, v199
	v_and_b32_e32 v9, 3, v5
	v_add_u32_e32 v9, s11, v9
	v_cvt_f32_ubyte0_e32 v9, v9
	v_mul_f32_e32 v11, -0.5, v9
	s_mov_b32 s14, 0xc2fc0000
	v_cmp_gt_f32_e32 vcc, s14, v11
	v_cvt_f32_u32_e32 v169, v7
	v_not_b32_e32 v7, 63
	v_cndmask_b32_e32 v11, 0, v227, vcc
	v_fmac_f32_e32 v11, -0.5, v9
	v_exp_f32_e32 v9, v11
	v_cndmask_b32_e32 v7, 0, v7, vcc
	v_ldexp_f32 v11, v9, v7
	v_pk_mul_f32 v[10:11], v[10:11], v[168:169]
	s_nop 0
	v_sub_f32_e32 v9, v10, v11
	s_branch .LBB0_528

.LBB0_543:
	v_ashrrev_i32_e32 v0, 6, v34
	s_movk_i32 s6, 0x220
	v_mul_lo_u32 v3, v0, s6
	v_mov_b32_e32 v0, 0
	v_mov_b32_e32 v198, 0
	v_mov_b32_e32 v199, 0
	v_mov_b32_e32 v200, 0
	s_movk_i32 s6, 0x84
	v_mov_b32_e32 v5, v4
.LBB0_544:
	v_add_u32_e32 v12, 0, v3
	v_add_u32_e32 v6, 0x11c20, v12
	v_add_u32_e32 v13, 0, v5
	v_add_u32_e32 v14, 0x400, v13
	v_add_u32_e32 v7, 0x800, v13
	ds_read_b128 v[146:149], v6
	ds_read_b128 v[150:153], v6 offset:16
	ds_read_b128 v[154:157], v6 offset:32
	ds_read2_b32 v[158:159], v13 offset1:65
	ds_read2_b32 v[160:161], v13 offset0:130 offset1:195
	ds_read2_b32 v[162:163], v14 offset0:4 offset1:69
	ds_read2_b32 v[164:165], v14 offset0:134 offset1:199
	ds_read2_b32 v[182:183], v7 offset0:8 offset1:73
	ds_read2_b32 v[184:185], v7 offset0:138 offset1:203
	s_add_i32 s6, s6, -12
	v_add_u32_e32 v5, 0xc30, v5
	v_add_u32_e32 v3, 48, v3
	s_cmp_lg_u32 s6, 0
	s_waitcnt lgkmcnt(0)
	v_fmac_f32_e32 v0, v146, v158
	v_fmac_f32_e32 v198, v147, v159
	v_fmac_f32_e32 v199, v148, v160
	v_fmac_f32_e32 v200, v149, v161
	v_fmac_f32_e32 v0, v150, v162
	v_fmac_f32_e32 v198, v151, v163
	v_fmac_f32_e32 v199, v152, v164
	v_fmac_f32_e32 v200, v153, v165
	v_fmac_f32_e32 v0, v154, v182
	v_fmac_f32_e32 v198, v155, v183
	v_fmac_f32_e32 v199, v156, v184
	v_fmac_f32_e32 v200, v157, v185
	s_cbranch_scc1 .LBB0_544
	v_add_f32_e32 v0, v0, v198
	v_add_f32_e32 v199, v199, v200
	s_nop 0
	v_add_f32_e32 v0, v0, v199
	v_cvt_pk_bf16_f32 v5, v0, v1
	v_ashrrev_i32_e32 v0, 8, v34
	v_and_b32_e32 v3, 0xc0, v34
	v_add_u32_e32 v0, s13, v0
	v_or_b32_e32 v3, s12, v3
	v_mov_b64_e32 v[6:7], s[88:89]
	v_mad_i64_i32 v[6:7], s[6:7], v0, s66, v[6:7]
	v_lshlrev_b32_e32 v0, 1, v3
	v_lshl_add_u64 v[6:7], v[6:7], 0, v[0:1]
	v_mov_b32_e32 v3, v1
	v_lshl_add_u64 v[6:7], v[6:7], 0, v[2:3]
	v_add_co_u32_e32 v6, vcc, 0x2000, v6
	s_movk_i32 s6, 0x1ff
	s_nop 0
	v_addc_co_u32_e32 v7, vcc, 0, v7, vcc
	v_add_u32_e32 v0, 0x200, v34
	v_cmp_lt_i32_e32 vcc, s6, v34
	s_or_b64 s[0:1], vcc, s[0:1]
	v_mov_b32_e32 v34, v0
	flat_store_short v[6:7], v5 offset:3104
	s_andn2_b64 exec, exec, s[0:1]
	s_cbranch_execnz .LBB0_543
